# lever 4 mirror: one static s_setprio 1 for the wave half wr=0 (the half that skips the extra entry barrier) at each GEMM phase entry
# baseline (speedup 1.0000x reference)
; #define PG8_STAGE(bufoff, gbase, voff) do { _Pragma("unroll") for (int _i = 0; _i < 2; ++_i) \
;         __builtin_amdgcn_global_load_lds((const unsigned*)((const char*)(gbase) + (voff)[_i]), (PG8_LAS unsigned*)(lds + (bufoff) + ldsw + _i * 8192), 16, 0, 0); } while (0)
; #define PG8_BAR __builtin_amdgcn_s_barrier()
; template <class Epi, class Sched, bool ALIGN_EPI = false, bool SP2 = false>
; __device__ __forceinline__ void gemm_phase(PG8_LAS unsigned char* lds, const Gemm g, const Sched& S, const Epi& E) {
;     ...
;         PG8_STAGE(PG8_SB(0, 0), cB, voffB); PG8_STAGE(PG8_SB(0, 1), cB + hstep, voffB); PG8_STAGE(PG8_SA(0, 0), cA, voffA); PG8_STAGE(PG8_SA(0, 1), cA + hstep, voffA);
;         if (wr == 1) PG8_BAR;
.LBB0_176:
	s_waitcnt lgkmcnt(0)
	s_barrier
	s_getreg_b32 s5, hwreg(HW_REG_HW_ID, 0, 6)
	s_and_b32 s5, s5, 63
	s_lshl_b32 s5, s5, 2
	s_or_b32 s5, s5, 0x25000
	v_mov_b32_e32 v1, s5
	ds_read_b32 v1, v1
	v_readlane_b32 s8, v253, 28
	v_mbcnt_lo_u32_b32 v2, -1, 0
	v_mbcnt_hi_u32_b32 v2, -1, v2
	v_readlane_b32 s9, v253, 29
	s_andn2_b64 vcc, exec, s[8:9]
	s_waitcnt lgkmcnt(0)
	v_readfirstlane_b32 s5, v1
	s_waitcnt vmcnt(5)
	s_nop 0
	v_lshl_add_u32 v12, s5, 6, v2
	s_nop 0
	v_readfirstlane_b32 s12, v12
	s_cbranch_vccnz .LBB0_258
	v_lshlrev_b32_e32 v1, 4, v12
	v_add_u32_e32 v2, 0x2000, v1
	v_ashrrev_i32_e32 v3, 31, v2
	v_lshrrev_b32_e32 v3, 22, v3
	v_add_u32_e32 v3, v2, v3
	v_ashrrev_i32_e32 v6, 10, v3
	v_mul_i32_i24_e32 v3, 0x400, v6
	v_sub_u32_e32 v2, v2, v3
	v_lshrrev_b32_e32 v3, 4, v2
	v_bitop3_b32 v2, v3, v2, 32 bitop3:0x6c
	v_ashrrev_i32_e32 v3, 31, v2
	v_lshrrev_b32_e32 v3, 26, v3
	v_add_u32_e32 v3, v2, v3
	v_lshlrev_b32_e32 v4, 3, v6
	v_ashrrev_i32_e32 v7, 6, v3
	v_and_b32_e32 v4, -16, v4
	v_add_u32_e32 v4, v7, v4
	v_and_b32_e32 v5, 3, v7
	s_mov_b32 s8, 0x1fffe0
	v_lshrrev_b32_e32 v8, 2, v4
	v_lshlrev_b32_e32 v9, 1, v4
	v_and_b32_e32 v3, 0xc0, v3
	v_and_or_b32 v5, v4, s8, v5
	v_and_b32_e32 v8, 4, v8
	v_and_b32_e32 v9, 24, v9
	v_sub_u32_e32 v2, v2, v3
	v_or3_b32 v5, v5, v8, v9
	v_lshlrev_b32_e32 v8, 5, v6
	v_ashrrev_i16_sdwa v2, v252, sext(v2) dst_sel:DWORD dst_unused:UNUSED_PAD src0_sel:DWORD src1_sel:BYTE_0
	v_and_b32_e32 v9, 32, v8
	v_bfe_i32 v8, v2, 0, 16
	v_add_lshl_u32 v2, v9, v8, 1
	v_lshl_add_u32 v14, v5, 11, v2
	v_lshl_add_u32 v166, v4, 11, v2
	v_bfe_i32 v2, v12, 27, 1
	v_lshrrev_b32_e32 v2, 22, v2
	v_add_u32_e32 v2, v1, v2
	v_and_b32_e32 v2, 0xfffffc00, v2
	v_sub_u32_e32 v1, v1, v2
	v_lshrrev_b32_e32 v2, 4, v1
	v_ashrrev_i32_e32 v3, 31, v12
	v_bitop3_b32 v1, v2, v1, 32 bitop3:0x6c
	v_lshrrev_b32_e32 v3, 26, v3
	v_ashrrev_i32_e32 v2, 31, v1
	v_add_u32_e32 v3, v12, v3
	v_lshrrev_b32_e32 v2, 26, v2
	v_ashrrev_i32_e32 v10, 6, v3
	v_add_u32_e32 v2, v1, v2
	v_lshlrev_b32_e32 v3, 3, v10
	v_ashrrev_i32_e32 v9, 6, v2
	v_and_b32_e32 v3, -16, v3
	v_add_u32_e32 v3, v9, v3
	v_and_b32_e32 v4, 3, v9
	v_lshrrev_b32_e32 v5, 2, v3
	v_lshlrev_b32_e32 v11, 1, v3
	v_and_b32_e32 v2, 0xc0, v2
	s_ashr_i32 s14, s12, 6
	v_and_or_b32 v4, v3, s8, v4
	v_and_b32_e32 v5, 4, v5
	v_and_b32_e32 v11, 24, v11
	v_sub_u32_e32 v1, v1, v2
	s_ashr_i32 s16, s12, 8
	s_lshl_b32 s5, s14, 10
	v_or3_b32 v4, v4, v5, v11
	v_lshlrev_b32_e32 v5, 5, v10
	v_ashrrev_i16_sdwa v1, v252, sext(v1) dst_sel:DWORD dst_unused:UNUSED_PAD src0_sel:DWORD src1_sel:BYTE_0
	v_readlane_b32 s8, v254, 37
	v_and_b32_e32 v5, 32, v5
	v_bfe_i32 v11, v1, 0, 16
	v_readlane_b32 s9, v254, 38
	s_add_u32 s22, s75, s8
	v_add_lshl_u32 v1, v5, v11, 1
	s_addc_u32 s23, s4, s9
	s_add_i32 s10, s5, 0
	v_lshl_add_u32 v168, v4, 11, v1
	s_add_i32 m0, s10, 0x10000
	v_lshl_add_u32 v170, v3, 11, v1
	global_load_lds_dwordx4 v168, s[22:23]
	s_add_i32 m0, s10, 0x12000
	s_add_u32 s8, s22, 0x40000
	global_load_lds_dwordx4 v14, s[22:23]
	s_addc_u32 s9, s23, 0
	s_add_i32 m0, s10, 0x14000
	s_add_i32 s11, s10, 0x2000
	global_load_lds_dwordx4 v168, s[8:9]
	s_add_i32 m0, s10, 0x16000
	s_add_i32 s26, s10, 0x4000
	global_load_lds_dwordx4 v14, s[8:9]
	v_readlane_b32 s8, v254, 43
	s_mov_b32 m0, s10
	v_readlane_b32 s9, v254, 44
	s_add_i32 s27, s10, 0x6000
	v_mov_b32_e32 v169, v0
	s_waitcnt vmcnt(0)
	v_mov_b32_e32 v15, v0
	s_cmp_eq_u32 s16, 1
	v_lshl_add_u64 v[2:3], s[22:23], 0, v[168:169]
	global_load_lds_dwordx4 v170, s[8:9]
	s_mov_b32 m0, s11
	v_lshl_add_u64 v[4:5], s[22:23], 0, v[14:15]
	global_load_lds_dwordx4 v166, s[8:9]
	v_readlane_b32 s8, v254, 45
	s_mov_b32 m0, s26
	v_readlane_b32 s9, v254, 46
	s_nop 4
	global_load_lds_dwordx4 v170, s[8:9]
	s_mov_b32 m0, s27
	s_nop 0
	global_load_lds_dwordx4 v166, s[8:9]
	s_cselect_b64 s[8:9], -1, 0
	s_cmp_lg_u32 s16, 1
	s_cbranch_scc1 .Lprio_179
	s_barrier
	s_branch .LBB0_179
.Lprio_179:
	s_setprio 1

; #define PG8_STAGE(bufoff, gbase, voff) do { _Pragma("unroll") for (int _i = 0; _i < 2; ++_i) \
;         __builtin_amdgcn_global_load_lds((const unsigned*)((const char*)(gbase) + (voff)[_i]), (PG8_LAS unsigned*)(lds + (bufoff) + ldsw + _i * 8192), 16, 0, 0); } while (0)
; #define PG8_BAR __builtin_amdgcn_s_barrier()
; template <class Epi, class Sched, bool ALIGN_EPI = false, bool SP2 = false>
; __device__ __forceinline__ void gemm_phase(PG8_LAS unsigned char* lds, const Gemm g, const Sched& S, const Epi& E) {
;     ...
;         PG8_STAGE(PG8_SB(0, 0), cB, voffB); PG8_STAGE(PG8_SB(0, 1), cB + hstep, voffB); PG8_STAGE(PG8_SA(0, 0), cA, voffA); PG8_STAGE(PG8_SA(0, 1), cA + hstep, voffA);
;         if (wr == 1) PG8_BAR;
.LBB0_259:
	s_and_b64 vcc, exec, s[8:9]
	s_cbranch_vccz .LBB0_340
	s_waitcnt lgkmcnt(0)
	v_readfirstlane_b32 s5, v17
	v_readlane_b32 s8, v253, 28
	v_mbcnt_lo_u32_b32 v1, -1, 0
	v_mbcnt_hi_u32_b32 v1, -1, v1
	v_readlane_b32 s9, v253, 29
	v_lshl_add_u32 v2, s5, 6, v1
	s_andn2_b64 vcc, exec, s[8:9]
	v_readfirstlane_b32 s12, v2
	s_cbranch_vccnz .LBB0_340
	v_lshlrev_b32_e32 v1, 4, v2
	v_add_u32_e32 v4, 0x2000, v1
	v_ashrrev_i32_e32 v3, 31, v4
	v_lshrrev_b32_e32 v3, 22, v3
	v_add_u32_e32 v3, v4, v3
	v_ashrrev_i32_e32 v3, 10, v3
	v_mul_i32_i24_e32 v5, 0x400, v3
	v_sub_u32_e32 v4, v4, v5
	v_lshrrev_b32_e32 v5, 4, v4
	v_bitop3_b32 v5, v5, v4, 32 bitop3:0x6c
	v_ashrrev_i32_e32 v4, 31, v5
	v_lshrrev_b32_e32 v4, 26, v4
	v_add_u32_e32 v6, v5, v4
	v_lshlrev_b32_e32 v7, 3, v3
	v_ashrrev_i32_e32 v4, 6, v6
	v_and_b32_e32 v7, -16, v7
	v_add_u32_e32 v7, v4, v7
	v_and_b32_e32 v8, 3, v4
	s_mov_b32 s8, 0x1fffe0
	v_lshrrev_b32_e32 v9, 2, v7
	v_lshlrev_b32_e32 v10, 1, v7
	v_and_b32_e32 v6, 0xc0, v6
	v_and_or_b32 v8, v7, s8, v8
	v_and_b32_e32 v9, 4, v9
	v_and_b32_e32 v10, 24, v10
	v_sub_u32_e32 v5, v5, v6
	v_or3_b32 v8, v8, v9, v10
	v_lshlrev_b32_e32 v9, 5, v3
	v_ashrrev_i16_sdwa v5, v252, sext(v5) dst_sel:DWORD dst_unused:UNUSED_PAD src0_sel:DWORD src1_sel:BYTE_0
	v_and_b32_e32 v9, 32, v9
	v_bfe_i32 v5, v5, 0, 16
	v_add_lshl_u32 v6, v9, v5, 1
	v_lshl_add_u32 v14, v8, 11, v6
	v_lshl_add_u32 v134, v7, 11, v6
	v_bfe_i32 v6, v2, 27, 1
	v_lshrrev_b32_e32 v6, 22, v6
	v_add_u32_e32 v6, v1, v6
	v_and_b32_e32 v6, 0xfffffc00, v6
	v_sub_u32_e32 v1, v1, v6
	v_lshrrev_b32_e32 v6, 4, v1
	v_ashrrev_i32_e32 v7, 31, v2
	v_bitop3_b32 v1, v6, v1, 32 bitop3:0x6c
	v_lshrrev_b32_e32 v7, 26, v7
	v_ashrrev_i32_e32 v6, 31, v1
	v_add_u32_e32 v7, v2, v7
	v_lshrrev_b32_e32 v6, 26, v6
	v_ashrrev_i32_e32 v7, 6, v7
	v_add_u32_e32 v8, v1, v6
	v_lshlrev_b32_e32 v9, 3, v7
	v_ashrrev_i32_e32 v6, 6, v8
	v_and_b32_e32 v9, -16, v9
	v_add_u32_e32 v9, v6, v9
	v_and_b32_e32 v10, 3, v6
	v_lshrrev_b32_e32 v11, 2, v9
	v_lshlrev_b32_e32 v12, 1, v9
	v_and_b32_e32 v8, 0xc0, v8
	s_ashr_i32 s14, s12, 6
	v_and_or_b32 v10, v9, s8, v10
	v_and_b32_e32 v11, 4, v11
	v_and_b32_e32 v12, 24, v12
	v_sub_u32_e32 v1, v1, v8
	s_ashr_i32 s15, s12, 8
	s_lshl_b32 s5, s14, 10
	v_or3_b32 v10, v10, v11, v12
	v_lshlrev_b32_e32 v11, 5, v7
	v_ashrrev_i16_sdwa v1, v252, sext(v1) dst_sel:DWORD dst_unused:UNUSED_PAD src0_sel:DWORD src1_sel:BYTE_0
	v_readlane_b32 s8, v254, 37
	v_and_b32_e32 v11, 32, v11
	v_bfe_i32 v8, v1, 0, 16
	v_readlane_b32 s9, v254, 38
	s_add_u32 s22, s75, s8
	v_add_lshl_u32 v1, v11, v8, 1
	s_addc_u32 s23, s4, s9
	s_add_i32 s10, s5, 0
	v_lshl_add_u32 v136, v10, 11, v1
	s_add_i32 m0, s10, 0x10000
	v_lshl_add_u32 v138, v9, 11, v1
	global_load_lds_dwordx4 v136, s[22:23]
	s_add_i32 m0, s10, 0x12000
	s_add_u32 s8, s22, 0x40000
	global_load_lds_dwordx4 v14, s[22:23]
	s_addc_u32 s9, s23, 0
	s_add_i32 m0, s10, 0x14000
	s_add_i32 s11, s10, 0x2000
	global_load_lds_dwordx4 v136, s[8:9]
	s_add_i32 m0, s10, 0x16000
	s_add_i32 s20, s10, 0x4000
	global_load_lds_dwordx4 v14, s[8:9]
	v_readlane_b32 s8, v254, 49
	s_mov_b32 m0, s10
	v_readlane_b32 s9, v254, 50
	s_add_i32 s26, s10, 0x6000
	s_cmp_eq_u32 s15, 1
	s_nop 2
	global_load_lds_dwordx4 v138, s[8:9]
	s_mov_b32 m0, s11
	s_nop 0
	global_load_lds_dwordx4 v134, s[8:9]
	v_readlane_b32 s8, v254, 51
	s_mov_b32 m0, s20
	v_readlane_b32 s9, v254, 52
	s_nop 4
	global_load_lds_dwordx4 v138, s[8:9]
	s_mov_b32 m0, s26
	s_nop 0
	global_load_lds_dwordx4 v134, s[8:9]
	s_cselect_b64 s[8:9], -1, 0
	s_cmp_lg_u32 s15, 1
	s_cbranch_scc1 .Lprio_263
	s_barrier
	s_branch .LBB0_263

; #define PG8_STAGE(bufoff, gbase, voff) do { _Pragma("unroll") for (int _i = 0; _i < 2; ++_i) \
;         __builtin_amdgcn_global_load_lds((const unsigned*)((const char*)(gbase) + (voff)[_i]), (PG8_LAS unsigned*)(lds + (bufoff) + ldsw + _i * 8192), 16, 0, 0); } while (0)
; #define PG8_BAR __builtin_amdgcn_s_barrier()
; template <class Epi, class Sched, bool ALIGN_EPI = false, bool SP2 = false>
; __device__ __forceinline__ void gemm_phase(PG8_LAS unsigned char* lds, const Gemm g, const Sched& S, const Epi& E) {
;     ...
;         PG8_STAGE(PG8_SB(0, 0), cB, voffB); PG8_STAGE(PG8_SB(0, 1), cB + hstep, voffB); PG8_STAGE(PG8_SA(0, 0), cA, voffA); PG8_STAGE(PG8_SA(0, 1), cA + hstep, voffA);
;         if (wr == 1) PG8_BAR;
.LBB0_771:
	s_waitcnt lgkmcnt(0)
	s_barrier
	s_getreg_b32 s8, hwreg(HW_REG_HW_ID, 0, 6)
	s_and_b32 s8, s8, 63
	s_lshl_b32 s8, s8, 2
	s_or_b32 s8, s8, 0x25000
	v_mov_b32_e32 v1, s8
	ds_read_b32 v1, v1
	v_mbcnt_lo_u32_b32 v2, -1, 0
	v_mbcnt_hi_u32_b32 v2, -1, v2
	s_waitcnt lgkmcnt(0)
	v_readfirstlane_b32 s8, v1
	s_waitcnt vmcnt(5)
	s_nop 0
	v_lshl_add_u32 v11, s8, 6, v2
	v_readlane_b32 s8, v254, 24
	v_readlane_b32 s9, v254, 25
	s_andn2_b64 vcc, exec, s[8:9]
	v_readfirstlane_b32 s14, v11
	s_cbranch_vccnz .LBB0_809
	v_lshlrev_b32_e32 v2, 4, v11
	v_add_u32_e32 v3, 0x2000, v2
	v_ashrrev_i32_e32 v1, 31, v3
	v_lshrrev_b32_e32 v1, 22, v1
	v_add_u32_e32 v1, v3, v1
	v_ashrrev_i32_e32 v1, 10, v1
	v_mul_i32_i24_e32 v4, 0x400, v1
	v_sub_u32_e32 v3, v3, v4
	v_lshrrev_b32_e32 v4, 4, v3
	v_bitop3_b32 v3, v4, v3, 32 bitop3:0x6c
	v_ashrrev_i32_e32 v4, 31, v3
	v_lshrrev_b32_e32 v4, 26, v4
	v_add_u32_e32 v4, v3, v4
	v_lshlrev_b32_e32 v5, 3, v1
	v_ashrrev_i32_e32 v6, 6, v4
	v_and_b32_e32 v5, -16, v5
	v_add_u32_e32 v5, v6, v5
	v_and_b32_e32 v7, 3, v6
	s_mov_b32 s8, 0x1fffe0
	v_lshrrev_b32_e32 v8, 2, v5
	v_lshlrev_b32_e32 v9, 1, v5
	v_and_b32_e32 v4, 0xc0, v4
	v_and_or_b32 v7, v5, s8, v7
	v_and_b32_e32 v8, 4, v8
	v_and_b32_e32 v9, 24, v9
	v_sub_u32_e32 v3, v3, v4
	v_or3_b32 v8, v7, v8, v9
	v_lshlrev_b32_e32 v7, 5, v1
	v_ashrrev_i16_sdwa v3, v252, sext(v3) dst_sel:DWORD dst_unused:UNUSED_PAD src0_sel:DWORD src1_sel:BYTE_0
	v_and_b32_e32 v9, 32, v7
	v_bfe_i32 v7, v3, 0, 16
	v_add_lshl_u32 v3, v9, v7, 1
	v_lshl_add_u32 v14, v8, 11, v3
	v_lshl_add_u32 v190, v5, 11, v3
	v_bfe_i32 v3, v11, 27, 1
	v_lshrrev_b32_e32 v3, 22, v3
	v_add_u32_e32 v3, v2, v3
	v_and_b32_e32 v3, 0xfffffc00, v3
	v_sub_u32_e32 v2, v2, v3
	v_lshrrev_b32_e32 v3, 4, v2
	v_ashrrev_i32_e32 v4, 31, v11
	v_bitop3_b32 v2, v3, v2, 32 bitop3:0x6c
	v_lshrrev_b32_e32 v4, 26, v4
	v_ashrrev_i32_e32 v3, 31, v2
	v_add_u32_e32 v4, v11, v4
	v_lshrrev_b32_e32 v3, 26, v3
	v_ashrrev_i32_e32 v9, 6, v4
	v_add_u32_e32 v3, v2, v3
	v_lshlrev_b32_e32 v4, 3, v9
	v_ashrrev_i32_e32 v8, 6, v3
	v_and_b32_e32 v4, -16, v4
	v_add_u32_e32 v4, v8, v4
	v_and_b32_e32 v5, 3, v8
	v_lshrrev_b32_e32 v10, 2, v4
	v_lshlrev_b32_e32 v12, 1, v4
	v_and_b32_e32 v3, 0xc0, v3
	s_ashr_i32 s15, s14, 6
	v_and_or_b32 v5, v4, s8, v5
	v_and_b32_e32 v10, 4, v10
	v_and_b32_e32 v12, 24, v12
	v_sub_u32_e32 v2, v2, v3
	s_ashr_i32 s12, s14, 8
	s_lshl_b32 s11, s15, 10
	v_or3_b32 v5, v5, v10, v12
	v_lshlrev_b32_e32 v10, 5, v9
	v_ashrrev_i16_sdwa v2, v252, sext(v2) dst_sel:DWORD dst_unused:UNUSED_PAD src0_sel:DWORD src1_sel:BYTE_0
	v_readlane_b32 s8, v254, 55
	v_and_b32_e32 v12, 32, v10
	v_bfe_i32 v10, v2, 0, 16
	v_readlane_b32 s9, v254, 56
	s_add_u32 s22, s5, s8
	v_add_lshl_u32 v2, v12, v10, 1
	s_addc_u32 s23, s10, s9
	s_add_i32 s28, s11, 0
	v_lshl_add_u32 v192, v5, 11, v2
	s_add_i32 m0, s28, 0x10000
	v_lshl_add_u32 v194, v4, 11, v2
	global_load_lds_dwordx4 v192, s[22:23]
	s_add_i32 m0, s28, 0x12000
	s_add_u32 s8, s22, 0x40000
	global_load_lds_dwordx4 v14, s[22:23]
	s_addc_u32 s9, s23, 0
	s_add_i32 m0, s28, 0x14000
	s_add_i32 s33, s28, 0x2000
	global_load_lds_dwordx4 v192, s[8:9]
	s_add_i32 m0, s28, 0x16000
	s_add_i32 s49, s28, 0x4000
	global_load_lds_dwordx4 v14, s[8:9]
	v_readlane_b32 s8, v254, 59
	s_mov_b32 m0, s28
	v_readlane_b32 s9, v254, 60
	s_add_i32 s71, s28, 0x6000
	v_mov_b32_e32 v193, v0
	s_waitcnt vmcnt(0)
	v_mov_b32_e32 v15, v0
	s_cmp_eq_u32 s12, 1
	v_lshl_add_u64 v[2:3], s[22:23], 0, v[192:193]
	global_load_lds_dwordx4 v194, s[8:9]
	s_mov_b32 m0, s33
	v_lshl_add_u64 v[4:5], s[22:23], 0, v[14:15]
	global_load_lds_dwordx4 v190, s[8:9]
	v_readlane_b32 s8, v254, 61
	s_mov_b32 m0, s49
	v_readlane_b32 s9, v254, 62
	s_nop 4
	global_load_lds_dwordx4 v194, s[8:9]
	s_mov_b32 m0, s71
	s_nop 0
	global_load_lds_dwordx4 v190, s[8:9]
	s_cselect_b64 s[8:9], -1, 0
	s_cmp_lg_u32 s12, 1
	s_cbranch_scc1 .Lprio_774
	s_barrier
	s_branch .LBB0_774

; #define PG8_STAGE(bufoff, gbase, voff) do { _Pragma("unroll") for (int _i = 0; _i < 2; ++_i) \
;         __builtin_amdgcn_global_load_lds((const unsigned*)((const char*)(gbase) + (voff)[_i]), (PG8_LAS unsigned*)(lds + (bufoff) + ldsw + _i * 8192), 16, 0, 0); } while (0)
; #define PG8_BAR __builtin_amdgcn_s_barrier()
; template <class Epi, class Sched, bool ALIGN_EPI = false, bool SP2 = false>
; __device__ __forceinline__ void gemm_phase(PG8_LAS unsigned char* lds, const Gemm g, const Sched& S, const Epi& E) {
;     ...
;         PG8_STAGE(PG8_SB(0, 0), cB, voffB); PG8_STAGE(PG8_SB(0, 1), cB + hstep, voffB); PG8_STAGE(PG8_SA(0, 0), cA, voffA); PG8_STAGE(PG8_SA(0, 1), cA + hstep, voffA);
;         if (wr == 1) PG8_BAR;
.LBB0_810:
	s_and_b64 vcc, exec, s[8:9]
	s_cbranch_vccz .LBB0_847
	s_waitcnt lgkmcnt(0)
	v_readfirstlane_b32 s8, v17
	v_mbcnt_lo_u32_b32 v1, -1, 0
	v_mbcnt_hi_u32_b32 v1, -1, v1
	s_nop 1
	v_lshl_add_u32 v7, s8, 6, v1
	v_readlane_b32 s8, v254, 24
	v_readlane_b32 s9, v254, 25
	s_andn2_b64 vcc, exec, s[8:9]
	v_readfirstlane_b32 s12, v7
	s_cbranch_vccnz .LBB0_847
	v_lshlrev_b32_e32 v4, 4, v7
	v_add_u32_e32 v2, 0x2000, v4
	v_ashrrev_i32_e32 v1, 31, v2
	v_lshrrev_b32_e32 v1, 22, v1
	v_add_u32_e32 v1, v2, v1
	v_ashrrev_i32_e32 v1, 10, v1
	v_mul_i32_i24_e32 v3, 0x400, v1
	v_sub_u32_e32 v2, v2, v3
	v_lshrrev_b32_e32 v3, 4, v2
	v_bitop3_b32 v3, v3, v2, 32 bitop3:0x6c
	v_ashrrev_i32_e32 v2, 31, v3
	v_lshrrev_b32_e32 v2, 26, v2
	v_add_u32_e32 v5, v3, v2
	v_lshlrev_b32_e32 v6, 3, v1
	v_ashrrev_i32_e32 v2, 6, v5
	v_and_b32_e32 v6, -16, v6
	v_add_u32_e32 v6, v2, v6
	v_and_b32_e32 v8, 3, v2
	s_mov_b32 s8, 0x1fffe0
	v_lshrrev_b32_e32 v9, 2, v6
	v_lshlrev_b32_e32 v10, 1, v6
	v_and_b32_e32 v5, 0xc0, v5
	v_and_or_b32 v8, v6, s8, v8
	v_and_b32_e32 v9, 4, v9
	v_and_b32_e32 v10, 24, v10
	v_sub_u32_e32 v3, v3, v5
	v_or3_b32 v8, v8, v9, v10
	v_lshlrev_b32_e32 v9, 5, v1
	v_ashrrev_i16_sdwa v3, v252, sext(v3) dst_sel:DWORD dst_unused:UNUSED_PAD src0_sel:DWORD src1_sel:BYTE_0
	v_and_b32_e32 v9, 32, v9
	v_bfe_i32 v3, v3, 0, 16
	v_add_lshl_u32 v5, v9, v3, 1
	v_lshl_add_u32 v14, v8, 11, v5
	s_waitcnt vmcnt(0)
	v_lshl_add_u32 v158, v6, 11, v5
	v_bfe_i32 v5, v7, 27, 1
	v_lshrrev_b32_e32 v5, 22, v5
	v_add_u32_e32 v5, v4, v5
	v_and_b32_e32 v5, 0xfffffc00, v5
	v_sub_u32_e32 v4, v4, v5
	v_lshrrev_b32_e32 v5, 4, v4
	v_bitop3_b32 v6, v5, v4, 32 bitop3:0x6c
	v_ashrrev_i32_e32 v5, 31, v7
	v_lshrrev_b32_e32 v5, 26, v5
	v_ashrrev_i32_e32 v4, 31, v6
	v_add_u32_e32 v5, v7, v5
	v_lshrrev_b32_e32 v4, 26, v4
	v_ashrrev_i32_e32 v5, 6, v5
	v_add_u32_e32 v8, v6, v4
	v_lshlrev_b32_e32 v9, 3, v5
	v_ashrrev_i32_e32 v4, 6, v8
	v_and_b32_e32 v9, -16, v9
	v_add_u32_e32 v9, v4, v9
	v_and_b32_e32 v10, 3, v4
	v_lshrrev_b32_e32 v11, 2, v9
	v_lshlrev_b32_e32 v12, 1, v9
	v_and_b32_e32 v8, 0xc0, v8
	s_ashr_i32 s15, s12, 6
	v_and_or_b32 v10, v9, s8, v10
	v_and_b32_e32 v11, 4, v11
	v_and_b32_e32 v12, 24, v12
	v_sub_u32_e32 v6, v6, v8
	s_ashr_i32 s14, s12, 8
	s_lshl_b32 s11, s15, 10
	v_or3_b32 v10, v10, v11, v12
	v_lshlrev_b32_e32 v11, 5, v5
	v_ashrrev_i16_sdwa v6, v252, sext(v6) dst_sel:DWORD dst_unused:UNUSED_PAD src0_sel:DWORD src1_sel:BYTE_0
	v_readlane_b32 s8, v254, 55
	v_and_b32_e32 v11, 32, v11
	v_bfe_i32 v6, v6, 0, 16
	v_readlane_b32 s9, v254, 56
	s_add_u32 s22, s5, s8
	v_add_lshl_u32 v8, v11, v6, 1
	s_addc_u32 s23, s10, s9
	s_add_i32 s28, s11, 0
	v_lshl_add_u32 v160, v10, 11, v8
	s_add_i32 m0, s28, 0x10000
	v_lshl_add_u32 v162, v9, 11, v8
	global_load_lds_dwordx4 v160, s[22:23]
	s_add_i32 m0, s28, 0x12000
	s_add_u32 s8, s22, 0x40000
	global_load_lds_dwordx4 v14, s[22:23]
	s_addc_u32 s9, s23, 0
	s_add_i32 m0, s28, 0x14000
	s_add_i32 s33, s28, 0x2000
	global_load_lds_dwordx4 v160, s[8:9]
	s_add_i32 m0, s28, 0x16000
	s_add_i32 s49, s28, 0x4000
	global_load_lds_dwordx4 v14, s[8:9]
	v_readlane_b32 s8, v254, 59
	s_mov_b32 m0, s28
	v_readlane_b32 s9, v254, 60
	s_add_i32 s71, s28, 0x6000
	s_cmp_eq_u32 s14, 1
	s_nop 2
	global_load_lds_dwordx4 v162, s[8:9]
	s_mov_b32 m0, s33
	s_nop 0
	global_load_lds_dwordx4 v158, s[8:9]
	v_readlane_b32 s8, v254, 61
	s_mov_b32 m0, s49
	v_readlane_b32 s9, v254, 62
	s_nop 4
	global_load_lds_dwordx4 v162, s[8:9]
	s_mov_b32 m0, s71
	s_nop 0
	global_load_lds_dwordx4 v158, s[8:9]
	s_cselect_b64 s[8:9], -1, 0
	s_cmp_lg_u32 s14, 1
	s_cbranch_scc1 .Lprio_814
	s_barrier
	s_branch .LBB0_814

; #define PG8_STAGE(bufoff, gbase, voff) do { _Pragma("unroll") for (int _i = 0; _i < 2; ++_i) \
;         __builtin_amdgcn_global_load_lds((const unsigned*)((const char*)(gbase) + (voff)[_i]), (PG8_LAS unsigned*)(lds + (bufoff) + ldsw + _i * 8192), 16, 0, 0); } while (0)
; #define PG8_BAR __builtin_amdgcn_s_barrier()
; template <class Epi, class Sched, bool ALIGN_EPI = false, bool SP2 = false>
; __device__ __forceinline__ void gemm_phase(PG8_LAS unsigned char* lds, const Gemm g, const Sched& S, const Epi& E) {
;     ...
;         PG8_STAGE(PG8_SB(0, 0), cB, voffB); PG8_STAGE(PG8_SB(0, 1), cB + hstep, voffB); PG8_STAGE(PG8_SA(0, 0), cA, voffA); PG8_STAGE(PG8_SA(0, 1), cA + hstep, voffA);
;         if (wr == 1) PG8_BAR;
.LBB0_973:
	s_waitcnt lgkmcnt(0)
	s_barrier
	s_getreg_b32 s5, hwreg(HW_REG_HW_ID, 0, 6)
	s_and_b32 s5, s5, 63
	s_lshl_b32 s5, s5, 2
	s_or_b32 s5, s5, 0x25000
	v_mov_b32_e32 v1, s5
	ds_read_b32 v1, v1
	v_readlane_b32 s8, v254, 20
	v_mbcnt_lo_u32_b32 v2, -1, 0
	v_mbcnt_hi_u32_b32 v2, -1, v2
	v_readlane_b32 s9, v254, 21
	s_andn2_b64 vcc, exec, s[8:9]
	s_waitcnt lgkmcnt(0)
	v_readfirstlane_b32 s5, v1
	s_waitcnt vmcnt(5)
	s_nop 0
	v_lshl_add_u32 v12, s5, 6, v2
	s_nop 0
	v_readfirstlane_b32 s14, v12
	s_cbranch_vccnz .LBB0_995
	v_lshlrev_b32_e32 v1, 4, v12
	v_add_u32_e32 v2, 0x2000, v1
	v_ashrrev_i32_e32 v3, 31, v2
	v_lshrrev_b32_e32 v3, 22, v3
	v_add_u32_e32 v3, v2, v3
	v_ashrrev_i32_e32 v6, 10, v3
	v_mul_i32_i24_e32 v3, 0x400, v6
	v_sub_u32_e32 v2, v2, v3
	v_lshrrev_b32_e32 v3, 4, v2
	v_bitop3_b32 v2, v3, v2, 32 bitop3:0x6c
	v_ashrrev_i32_e32 v3, 31, v2
	v_lshrrev_b32_e32 v3, 26, v3
	v_add_u32_e32 v3, v2, v3
	v_lshlrev_b32_e32 v4, 3, v6
	v_ashrrev_i32_e32 v7, 6, v3
	v_and_b32_e32 v4, -16, v4
	v_add_u32_e32 v4, v7, v4
	v_and_b32_e32 v5, 3, v7
	s_mov_b32 s8, 0x1fffe0
	v_lshrrev_b32_e32 v8, 2, v4
	v_lshlrev_b32_e32 v9, 1, v4
	v_and_b32_e32 v3, 0xc0, v3
	v_and_or_b32 v5, v4, s8, v5
	v_and_b32_e32 v8, 4, v8
	v_and_b32_e32 v9, 24, v9
	v_sub_u32_e32 v2, v2, v3
	v_or3_b32 v5, v5, v8, v9
	v_lshlrev_b32_e32 v8, 5, v6
	v_ashrrev_i16_sdwa v2, v252, sext(v2) dst_sel:DWORD dst_unused:UNUSED_PAD src0_sel:DWORD src1_sel:BYTE_0
	v_and_b32_e32 v9, 32, v8
	v_bfe_i32 v8, v2, 0, 16
	v_add_lshl_u32 v2, v9, v8, 1
	v_lshl_add_u32 v14, v5, 11, v2
	v_lshl_add_u32 v166, v4, 11, v2
	v_bfe_i32 v2, v12, 27, 1
	v_lshrrev_b32_e32 v2, 22, v2
	v_add_u32_e32 v2, v1, v2
	v_and_b32_e32 v2, 0xfffffc00, v2
	v_sub_u32_e32 v1, v1, v2
	v_lshrrev_b32_e32 v2, 4, v1
	v_ashrrev_i32_e32 v3, 31, v12
	v_bitop3_b32 v1, v2, v1, 32 bitop3:0x6c
	v_lshrrev_b32_e32 v3, 26, v3
	v_ashrrev_i32_e32 v2, 31, v1
	v_add_u32_e32 v3, v12, v3
	v_lshrrev_b32_e32 v2, 26, v2
	v_ashrrev_i32_e32 v10, 6, v3
	v_add_u32_e32 v2, v1, v2
	v_lshlrev_b32_e32 v3, 3, v10
	v_ashrrev_i32_e32 v9, 6, v2
	v_and_b32_e32 v3, -16, v3
	s_ashr_i32 s15, s14, 6
	v_add_u32_e32 v3, v9, v3
	s_ashr_i32 s12, s14, 8
	s_lshl_b32 s5, s15, 10
	v_and_b32_e32 v4, 3, v9
	v_lshrrev_b32_e32 v5, 2, v3
	v_lshlrev_b32_e32 v11, 1, v3
	v_and_b32_e32 v2, 0xc0, v2
	s_add_u32 s10, s75, 0x800000
	v_and_or_b32 v4, v3, s8, v4
	v_and_b32_e32 v5, 4, v5
	v_and_b32_e32 v11, 24, v11
	v_sub_u32_e32 v1, v1, v2
	s_addc_u32 s11, s4, 0
	v_or3_b32 v4, v4, v5, v11
	v_lshlrev_b32_e32 v5, 5, v10
	v_ashrrev_i16_sdwa v1, v252, sext(v1) dst_sel:DWORD dst_unused:UNUSED_PAD src0_sel:DWORD src1_sel:BYTE_0
	v_readlane_b32 s8, v254, 27
	v_and_b32_e32 v5, 32, v5
	v_bfe_i32 v11, v1, 0, 16
	v_readlane_b32 s9, v254, 28
	s_add_u32 s22, s10, s8
	v_add_lshl_u32 v1, v5, v11, 1
	s_addc_u32 s23, s11, s9
	s_add_i32 s20, s5, 0
	v_lshl_add_u32 v168, v4, 11, v1
	s_add_i32 m0, s20, 0x10000
	v_lshl_add_u32 v170, v3, 11, v1
	global_load_lds_dwordx4 v168, s[22:23]
	s_add_i32 m0, s20, 0x12000
	s_add_u32 s8, s22, 0x40000
	global_load_lds_dwordx4 v14, s[22:23]
	s_addc_u32 s9, s23, 0
	s_add_i32 m0, s20, 0x14000
	s_add_i32 s26, s20, 0x2000
	global_load_lds_dwordx4 v168, s[8:9]
	s_add_i32 m0, s20, 0x16000
	s_add_i32 s27, s20, 0x4000
	global_load_lds_dwordx4 v14, s[8:9]
	v_readlane_b32 s8, v254, 33
	s_mov_b32 m0, s20
	v_readlane_b32 s9, v254, 34
	s_add_i32 s28, s20, 0x6000
	v_mov_b32_e32 v169, v0
	s_waitcnt vmcnt(0)
	v_mov_b32_e32 v15, v0
	s_cmp_eq_u32 s12, 1
	v_lshl_add_u64 v[2:3], s[22:23], 0, v[168:169]
	global_load_lds_dwordx4 v170, s[8:9]
	s_mov_b32 m0, s26
	v_lshl_add_u64 v[4:5], s[22:23], 0, v[14:15]
	global_load_lds_dwordx4 v166, s[8:9]
	v_readlane_b32 s8, v254, 35
	s_mov_b32 m0, s27
	v_readlane_b32 s9, v254, 36
	s_nop 4
	global_load_lds_dwordx4 v170, s[8:9]
	s_mov_b32 m0, s28
	s_nop 0
	global_load_lds_dwordx4 v166, s[8:9]
	s_cselect_b64 s[8:9], -1, 0
	s_cmp_lg_u32 s12, 1
	s_cbranch_scc1 .Lprio_976
	s_barrier
	s_branch .LBB0_976

; #define PG8_STAGE(bufoff, gbase, voff) do { _Pragma("unroll") for (int _i = 0; _i < 2; ++_i) \
;         __builtin_amdgcn_global_load_lds((const unsigned*)((const char*)(gbase) + (voff)[_i]), (PG8_LAS unsigned*)(lds + (bufoff) + ldsw + _i * 8192), 16, 0, 0); } while (0)
; #define PG8_BAR __builtin_amdgcn_s_barrier()
; template <class Epi, class Sched, bool ALIGN_EPI = false, bool SP2 = false>
; __device__ __forceinline__ void gemm_phase(PG8_LAS unsigned char* lds, const Gemm g, const Sched& S, const Epi& E) {
;     ...
;         PG8_STAGE(PG8_SB(0, 0), cB, voffB); PG8_STAGE(PG8_SB(0, 1), cB + hstep, voffB); PG8_STAGE(PG8_SA(0, 0), cA, voffA); PG8_STAGE(PG8_SA(0, 1), cA + hstep, voffA);
;         if (wr == 1) PG8_BAR;
.LBB0_1121:
	s_waitcnt lgkmcnt(0)
	s_barrier
	s_getreg_b32 s5, hwreg(HW_REG_HW_ID, 0, 6)
	s_and_b32 s5, s5, 63
	s_lshl_b32 s5, s5, 2
	s_or_b32 s5, s5, 0x25000
	v_mov_b32_e32 v1, s5
	ds_read_b32 v1, v1
	v_readlane_b32 s8, v254, 24
	v_mbcnt_lo_u32_b32 v2, -1, 0
	v_mbcnt_hi_u32_b32 v2, -1, v2
	v_readlane_b32 s9, v254, 25
	s_andn2_b64 vcc, exec, s[8:9]
	s_waitcnt lgkmcnt(0)
	v_readfirstlane_b32 s5, v1
	s_waitcnt vmcnt(5)
	s_nop 0
	v_lshl_add_u32 v11, s5, 6, v2
	s_nop 0
	v_readfirstlane_b32 s16, v11
	s_cbranch_vccnz .LBB0_1159
	v_lshlrev_b32_e32 v2, 4, v11
	v_add_u32_e32 v3, 0x2000, v2
	v_ashrrev_i32_e32 v1, 31, v3
	v_lshrrev_b32_e32 v1, 22, v1
	v_add_u32_e32 v1, v3, v1
	v_ashrrev_i32_e32 v1, 10, v1
	v_mul_i32_i24_e32 v4, 0x400, v1
	v_sub_u32_e32 v3, v3, v4
	v_lshrrev_b32_e32 v4, 4, v3
	v_bitop3_b32 v3, v4, v3, 32 bitop3:0x6c
	v_ashrrev_i32_e32 v4, 31, v3
	v_lshrrev_b32_e32 v4, 26, v4
	v_add_u32_e32 v4, v3, v4
	v_lshlrev_b32_e32 v5, 3, v1
	v_ashrrev_i32_e32 v6, 6, v4
	v_and_b32_e32 v5, -16, v5
	v_add_u32_e32 v5, v6, v5
	v_and_b32_e32 v7, 3, v6
	s_mov_b32 s8, 0x7ffe0
	v_lshrrev_b32_e32 v8, 2, v5
	v_lshlrev_b32_e32 v9, 1, v5
	v_and_b32_e32 v4, 0xc0, v4
	v_and_or_b32 v7, v5, s8, v7
	v_and_b32_e32 v8, 4, v8
	v_and_b32_e32 v9, 24, v9
	v_sub_u32_e32 v3, v3, v4
	v_or3_b32 v8, v7, v8, v9
	v_lshlrev_b32_e32 v7, 5, v1
	v_ashrrev_i16_sdwa v3, v252, sext(v3) dst_sel:DWORD dst_unused:UNUSED_PAD src0_sel:DWORD src1_sel:BYTE_0
	v_and_b32_e32 v9, 32, v7
	v_bfe_i32 v7, v3, 0, 16
	v_add_lshl_u32 v3, v9, v7, 1
	v_lshl_add_u32 v14, v8, 13, v3
	v_lshl_add_u32 v190, v5, 13, v3
	v_bfe_i32 v3, v11, 27, 1
	v_lshrrev_b32_e32 v3, 22, v3
	v_add_u32_e32 v3, v2, v3
	v_and_b32_e32 v3, 0xfffffc00, v3
	v_sub_u32_e32 v2, v2, v3
	v_lshrrev_b32_e32 v3, 4, v2
	v_ashrrev_i32_e32 v4, 31, v11
	v_bitop3_b32 v2, v3, v2, 32 bitop3:0x6c
	v_lshrrev_b32_e32 v4, 26, v4
	v_ashrrev_i32_e32 v3, 31, v2
	v_add_u32_e32 v4, v11, v4
	v_lshrrev_b32_e32 v3, 26, v3
	v_ashrrev_i32_e32 v9, 6, v4
	v_add_u32_e32 v3, v2, v3
	v_lshlrev_b32_e32 v4, 3, v9
	v_ashrrev_i32_e32 v8, 6, v3
	v_and_b32_e32 v4, -16, v4
	s_ashr_i32 s17, s16, 6
	v_add_u32_e32 v4, v8, v4
	s_ashr_i32 s12, s16, 8
	s_lshl_b32 s5, s17, 10
	v_and_b32_e32 v5, 3, v8
	v_lshrrev_b32_e32 v10, 2, v4
	v_lshlrev_b32_e32 v12, 1, v4
	v_and_b32_e32 v3, 0xc0, v3
	s_add_u32 s10, s75, 0x1000000
	v_and_or_b32 v5, v4, s8, v5
	v_and_b32_e32 v10, 4, v10
	v_and_b32_e32 v12, 24, v12
	v_sub_u32_e32 v2, v2, v3
	s_addc_u32 s4, s4, 0
	v_or3_b32 v5, v5, v10, v12
	v_lshlrev_b32_e32 v10, 5, v9
	v_ashrrev_i16_sdwa v2, v252, sext(v2) dst_sel:DWORD dst_unused:UNUSED_PAD src0_sel:DWORD src1_sel:BYTE_0
	v_readlane_b32 s8, v254, 63
	v_and_b32_e32 v12, 32, v10
	v_bfe_i32 v10, v2, 0, 16
	v_readlane_b32 s9, v255, 0
	s_add_u32 s22, s10, s8
	v_add_lshl_u32 v2, v12, v10, 1
	s_addc_u32 s23, s4, s9
	s_add_i32 s11, s5, 0
	v_lshl_add_u32 v192, v5, 13, v2
	s_add_i32 m0, s11, 0x10000
	v_lshl_add_u32 v194, v4, 13, v2
	global_load_lds_dwordx4 v192, s[22:23]
	s_add_i32 m0, s11, 0x12000
	s_add_u32 s8, s22, 0x100000
	global_load_lds_dwordx4 v14, s[22:23]
	s_addc_u32 s9, s23, 0
	s_add_i32 m0, s11, 0x14000
	s_add_i32 s28, s11, 0x2000
	global_load_lds_dwordx4 v192, s[8:9]
	s_add_i32 m0, s11, 0x16000
	s_add_i32 s33, s11, 0x4000
	global_load_lds_dwordx4 v14, s[8:9]
	v_readlane_b32 s8, v255, 3
	s_mov_b32 m0, s11
	v_readlane_b32 s9, v255, 4
	s_add_i32 s49, s11, 0x6000
	v_mov_b32_e32 v193, v0
	s_waitcnt vmcnt(0)
	v_mov_b32_e32 v15, v0
	s_cmp_eq_u32 s12, 1
	v_lshl_add_u64 v[2:3], s[22:23], 0, v[192:193]
	global_load_lds_dwordx4 v194, s[8:9]
	s_mov_b32 m0, s28
	v_lshl_add_u64 v[4:5], s[22:23], 0, v[14:15]
	global_load_lds_dwordx4 v190, s[8:9]
	v_readlane_b32 s8, v255, 5
	s_mov_b32 m0, s33
	v_readlane_b32 s9, v255, 6
	s_nop 4
	global_load_lds_dwordx4 v194, s[8:9]
	s_mov_b32 m0, s49
	s_nop 0
	global_load_lds_dwordx4 v190, s[8:9]
	s_cselect_b64 s[8:9], -1, 0
	s_cmp_lg_u32 s12, 1
	s_cbranch_scc1 .Lprio_1124
	s_barrier
	s_branch .LBB0_1124
